# ff1 tile order within an XCD: 4 M-tiles x 8 N-tiles per round (paired rounds) instead of 2 x 16, fewer distinct A/B tiles per k-step through L2
# speedup vs baseline: 1.0068x; 1.0057x over previous
; #define MFMA(a, b, c) __builtin_amdgcn_mfma_f32_32x32x16_bf16((a), (b), (c), 0, 0, 0)
; DI int crow(int reg, int h) { return (reg & 3) + 8 * (reg >> 2) + 4 * h; }
; template <int DQK>
; DI void attn_tile(const u16* __restrict__ q, int ldq, int qpos0, const Seg& s0, const Seg& s1, int nseg, bool has_sink,
;                   float sinkl2, u16* __restrict__ out, int ldo, char* lds) {
;     ...
;   auto compute = [&](int i) {
;     const Seg& sg = (i < nt0) ? s0 : s1;
;     const int off = ((i < nt0) ? i : i - nt0) << 6;
;     f32x16 sa = zero16(), sb = zero16();
; #pragma unroll
;     for (int ks = 0; ks < NKS; ++ks) {
;       bf16x8 a0 = *(const bf16x8*)(Ks + r * KST + ks * 16 + 8 * h);
;       bf16x8 a1 = *(const bf16x8*)(Ks + (32 + r) * KST + ks * 16 + 8 * h);
;       sa = MFMA(a0, qf[ks], sa);
;       sb = MFMA(a1, qf[ks], sb);
;     }
;     if (sg.masked) {
;       const int qpos = qpos0 + qi;
;       const int kb = sg.pos0 + off;
; #pragma unroll
;       for (int g = 0; g < 16; ++g) {
;         int d0 = kb + crow(g, h) - qpos, d1 = d0 + 32;
;         if (d0 > 128 || d0 < -128) sa[g] = -INFINITY;
;         if (d1 > 128 || d1 < -128) sb[g] = -INFINITY;
;       }
;     }
;     float mx = sa[0];
; #pragma unroll
;     for (int g = 1; g < 16; ++g) mx = fmaxf(mx, sa[g]);
; #pragma unroll
;     for (int g = 0; g < 16; ++g) mx = fmaxf(mx, sb[g]);
;     mx = fmaxf(mx, __shfl_xor(mx, 32));
;     const float mn = fmaxf(m, mx);
;     const float alpha = __builtin_amdgcn_exp2f(m - mn);
;     m = mn;
;     float ps = 0.f;
; #pragma unroll
;     for (int g = 0; g < 16; ++g) { sa[g] = __builtin_amdgcn_exp2f(sa[g] - mn); ps += sa[g]; }
; #pragma unroll
;     for (int g = 0; g < 16; ++g) { sb[g] = __builtin_amdgcn_exp2f(sb[g] - mn); ps += sb[g]; }
;     l = l * alpha + ps;
; #pragma unroll
;     for (int g = 0; g < 16; ++g) { o0[g] *= alpha; o1[g] *= alpha; }
.LBB0_602:
	s_add_i32 s22, s22, 2
	ds_read_b128 v[34:37], v130
	ds_read_b128 v[38:41], v130 offset:6656
	ds_read_b128 v[42:45], v130 offset:32
	s_waitcnt lgkmcnt(2)
	v_mfma_f32_32x32x16_bf16 v[50:65], v[34:37], v[66:69], 0
	ds_read_b128 v[34:37], v130 offset:6688
	v_max3_f32 v137, v184, v185, v186
	v_max3_f32 v137, v137, v187, v188
	v_max3_f32 v137, v137, v189, v190
	v_max3_f32 v137, v137, v191, v192
	s_waitcnt lgkmcnt(2)
	v_mfma_f32_32x32x16_bf16 v[218:233], v[38:41], v[66:69], 0
	ds_read_b128 v[38:41], v130 offset:64
	v_max3_f32 v137, v137, v193, v194
	v_max3_f32 v137, v137, v195, v196
	v_max3_f32 v137, v137, v197, v198
	v_max3_f32 v137, v137, v199, v146
	s_waitcnt lgkmcnt(2)
	v_mfma_f32_32x32x16_bf16 v[50:65], v[42:45], v[70:73], v[50:65]
	ds_read_b128 v[42:45], v130 offset:6720
	v_max3_f32 v137, v137, v147, v148
	v_max3_f32 v137, v137, v149, v150
	v_max3_f32 v137, v137, v151, v152
	v_max3_f32 v137, v137, v153, v154
	s_waitcnt lgkmcnt(2)
	v_mfma_f32_32x32x16_bf16 v[218:233], v[34:37], v[70:73], v[218:233]
	ds_read_b128 v[34:37], v130 offset:96
	v_max3_f32 v137, v137, v155, v156
	v_max3_f32 v137, v137, v157, v158
	v_max3_f32 v137, v137, v159, v160
	v_max3_f32 v137, v137, v161, v161
	s_waitcnt lgkmcnt(2)
	v_mfma_f32_32x32x16_bf16 v[50:65], v[38:41], v[74:77], v[50:65]
	ds_read_b128 v[38:41], v130 offset:6752
	ds_bpermute_b32 v139, v131, v137
	s_waitcnt lgkmcnt(0)
	v_max3_f32 v134, v135, v137, v139
	v_sub_f32_e32 v141, v135, v134
	v_mfma_f32_32x32x16_bf16 v[218:233], v[42:45], v[74:77], v[218:233]
	ds_read_b128 v[42:45], v130 offset:128
	v_exp_f32_e32 v140, v141
	v_mov_b32_e32 v144, v134
	v_mov_b32_e32 v145, v134
	v_sub_f32_e32 v184, v184, v134
	v_mfma_f32_32x32x16_bf16 v[50:65], v[34:37], v[78:81], v[50:65]
	ds_read_b128 v[34:37], v130 offset:6784
	v_sub_f32_e32 v185, v185, v134
	v_sub_f32_e32 v186, v186, v134
	v_sub_f32_e32 v187, v187, v134
	v_sub_f32_e32 v188, v188, v134
	v_mfma_f32_32x32x16_bf16 v[218:233], v[38:41], v[78:81], v[218:233]
	ds_read_b128 v[38:41], v130 offset:160
	v_sub_f32_e32 v189, v189, v134
	v_sub_f32_e32 v190, v190, v134
	v_sub_f32_e32 v191, v191, v134
	v_exp_f32_e32 v184, v184
	s_waitcnt lgkmcnt(2)
	v_mfma_f32_32x32x16_bf16 v[50:65], v[42:45], v[82:85], v[50:65]
	ds_read_b128 v[42:45], v130 offset:6816
	v_sub_f32_e32 v192, v192, v134
	v_sub_f32_e32 v193, v193, v134
	v_sub_f32_e32 v194, v194, v134
	v_sub_f32_e32 v195, v195, v134
	s_waitcnt lgkmcnt(2)
	v_mfma_f32_32x32x16_bf16 v[218:233], v[34:37], v[82:85], v[218:233]
	v_exp_f32_e32 v185, v185
	v_sub_f32_e32 v196, v196, v134
	v_sub_f32_e32 v197, v197, v134
	v_sub_f32_e32 v198, v198, v134
	s_waitcnt lgkmcnt(1)
	v_mfma_f32_32x32x16_bf16 v[50:65], v[38:41], v[86:89], v[50:65]
	v_sub_f32_e32 v199, v199, v134
	v_exp_f32_e32 v186, v186
	v_sub_f32_e32 v146, v146, v134
	v_sub_f32_e32 v147, v147, v134
	s_waitcnt lgkmcnt(0)
; #define MFMA(a, b, c) __builtin_amdgcn_mfma_f32_32x32x16_bf16((a), (b), (c), 0, 0, 0)
; #define ATT_VTR(p) __builtin_bit_cast(s16x4, __builtin_amdgcn_ds_read_tr16_b64_v4i16((__attribute__((address_space(3))) v4i16_t*)(p)))
; template <int DQK>
; DI void attn_tile(const u16* __restrict__ q, int ldq, int qpos0, const Seg& s0, const Seg& s1, int nseg, bool has_sink,
;                   float sinkl2, u16* __restrict__ out, int ldo, char* lds) {
;     ...
;     float mx = sa[0];
; #pragma unroll
;     for (int g = 1; g < 16; ++g) mx = fmaxf(mx, sa[g]);
; #pragma unroll
;     for (int g = 0; g < 16; ++g) mx = fmaxf(mx, sb[g]);
;     mx = fmaxf(mx, __shfl_xor(mx, 32));
;     const float mn = fmaxf(m, mx);
;     const float alpha = __builtin_amdgcn_exp2f(m - mn);
;     m = mn;
;     float ps = 0.f;
; #pragma unroll
;     for (int g = 0; g < 16; ++g) { sa[g] = __builtin_amdgcn_exp2f(sa[g] - mn); ps += sa[g]; }
; #pragma unroll
;     for (int g = 0; g < 16; ++g) { sb[g] = __builtin_amdgcn_exp2f(sb[g] - mn); ps += sb[g]; }
;     l = l * alpha + ps;
; #pragma unroll
;     for (int g = 0; g < 16; ++g) { o0[g] *= alpha; o1[g] *= alpha; }
; #pragma unroll
;     for (int kt = 0; kt < 2; ++kt) {
; #pragma unroll
;       for (int s = 0; s < 2; ++s) {
;         const f32x16& sv = kt == 0 ? sa : sb;
;         uint4 pu;
;         pu.x = pack2(sv[8 * s + 0], sv[8 * s + 1]); pu.y = pack2(sv[8 * s + 2], sv[8 * s + 3]);
;         pu.z = pack2(sv[8 * s + 4], sv[8 * s + 5]); pu.w = pack2(sv[8 * s + 6], sv[8 * s + 7]);
;         bf16x8 pf = __builtin_bit_cast(bf16x8, pu);
;         const lds_cptr vp = vp0 + (kt * 32 + 16 * s) * (VST * 2);
;         {
;           s16x4 lo = ATT_VTR(vp);
;           s16x4 hi = ATT_VTR(vp + 8 * VST * 2);
;           bf16x8 vf = __builtin_shufflevector(lo, hi, 0, 1, 2, 3, 4, 5, 6, 7);
;           o0 = MFMA(vf, pf, o0);
;         }
;         {
;           s16x4 lo = ATT_VTR(vp + 64);
;           s16x4 hi = ATT_VTR(vp + 8 * VST * 2 + 64);
;           bf16x8 vf = __builtin_shufflevector(lo, hi, 0, 1, 2, 3, 4, 5, 6, 7);
;           o1 = MFMA(vf, pf, o1);
;         }
;       }
;     }
;   };
;   ATT_LOADX(0, kreg0, kreg1, vreg0);
;   ATT_LOADX(1, krgB0, krgB1, vrgB0);
;   for (int i = 0; i < NT; i += 2) {
	v_mfma_f32_32x32x16_bf16 v[218:233], v[42:45], v[86:89], v[218:233]
	ds_read_b64_tr_b16 v[46:47], v133 offset:46080
	ds_read_b64_tr_b16 v[48:49], v133 offset:47616
	ds_read_b64_tr_b16 v[200:201], v133 offset:46144
	ds_read_b64_tr_b16 v[202:203], v133 offset:47680
	ds_read_b64_tr_b16 v[204:205], v133 offset:49152
	ds_read_b64_tr_b16 v[206:207], v133 offset:50688
	ds_read_b64_tr_b16 v[234:235], v133 offset:49216
	ds_read_b64_tr_b16 v[236:237], v133 offset:50752
	v_sub_f32_e32 v148, v148, v134
	v_sub_f32_e32 v149, v149, v134
	v_exp_f32_e32 v187, v187
	v_sub_f32_e32 v150, v150, v134
	v_sub_f32_e32 v151, v151, v134
	v_sub_f32_e32 v152, v152, v134
	v_sub_f32_e32 v153, v153, v134
	v_exp_f32_e32 v188, v188
	v_mul_f32_e32 v33, v140, v33
	v_mul_f32_e32 v32, v140, v32
	v_mul_f32_e32 v31, v140, v31
	v_mul_f32_e32 v30, v140, v30
	v_exp_f32_e32 v189, v189
	v_mul_f32_e32 v29, v140, v29
	v_mul_f32_e32 v28, v140, v28
	v_mul_f32_e32 v27, v140, v27
	v_mul_f32_e32 v26, v140, v26
	v_exp_f32_e32 v190, v190
	v_mul_f32_e32 v25, v140, v25
	v_mul_f32_e32 v24, v140, v24
	v_mul_f32_e32 v23, v140, v23
	v_mul_f32_e32 v22, v140, v22
	v_exp_f32_e32 v191, v191
	v_mul_f32_e32 v21, v140, v21
	v_mul_f32_e32 v20, v140, v20
	v_mul_f32_e32 v19, v140, v19
	v_mul_f32_e32 v18, v140, v18
	v_exp_f32_e32 v192, v192
	v_sub_f32_e32 v154, v154, v134
	v_sub_f32_e32 v155, v155, v134
	v_sub_f32_e32 v156, v156, v134
	v_sub_f32_e32 v157, v157, v134
	v_sub_f32_e32 v158, v158, v134
	v_exp_f32_e32 v193, v193
	v_sub_f32_e32 v159, v159, v134
	v_sub_f32_e32 v160, v160, v134
	v_sub_f32_e32 v161, v161, v134
	v_mul_f32_e32 v17, v140, v17
	v_mul_f32_e32 v16, v140, v16
	v_exp_f32_e32 v194, v194
	v_mul_f32_e32 v15, v140, v15
	v_mul_f32_e32 v14, v140, v14
	v_mul_f32_e32 v13, v140, v13
	v_mul_f32_e32 v12, v140, v12
	v_mul_f32_e32 v11, v140, v11
	v_exp_f32_e32 v195, v195
	v_mul_f32_e32 v10, v140, v10
	v_mul_f32_e32 v9, v140, v9
	v_mul_f32_e32 v8, v140, v8
	v_mul_f32_e32 v7, v140, v7
	v_mul_f32_e32 v6, v140, v6
	v_exp_f32_e32 v196, v196
	v_mul_f32_e32 v5, v140, v5
	v_mul_f32_e32 v4, v140, v4
	v_mul_f32_e32 v3, v140, v3
	v_mul_f32_e32 v2, v140, v2
	v_add_f32_e32 v238, v184, v185
	v_exp_f32_e32 v197, v197
	v_add_f32_e32 v238, v238, v186
	v_add_f32_e32 v238, v238, v187
	v_add_f32_e32 v238, v238, v188
	v_add_f32_e32 v238, v238, v189
	v_add_f32_e32 v238, v238, v190
	v_exp_f32_e32 v198, v198
	v_add_f32_e32 v238, v238, v191
	v_cvt_pk_bf16_f32 v184, v184, v185
	v_cvt_pk_bf16_f32 v185, v186, v187
	v_cvt_pk_bf16_f32 v186, v188, v189
	v_cvt_pk_bf16_f32 v187, v190, v191
	v_exp_f32_e32 v199, v199
	s_nop 0
	s_waitcnt lgkmcnt(6)
	v_mfma_f32_32x32x16_bf16 v[18:33], v[46:49], v[184:187], v[18:33]
	ds_read_b64_tr_b16 v[46:47], v133 offset:52224
	ds_read_b64_tr_b16 v[48:49], v133 offset:53760
	s_waitcnt lgkmcnt(6)
	v_mfma_f32_32x32x16_bf16 v[2:17], v[200:203], v[184:187], v[2:17]
	ds_read_b64_tr_b16 v[200:201], v133 offset:52288
	ds_read_b64_tr_b16 v[202:203], v133 offset:53824
	v_exp_f32_e32 v146, v146
	v_add_f32_e32 v238, v238, v192
	v_add_f32_e32 v238, v238, v193
	v_exp_f32_e32 v147, v147
	v_add_f32_e32 v238, v238, v194
	v_add_f32_e32 v238, v238, v195
	v_exp_f32_e32 v148, v148
	v_add_f32_e32 v238, v238, v196
	v_add_f32_e32 v238, v238, v197
	v_exp_f32_e32 v149, v149
	v_add_f32_e32 v238, v238, v198
	v_add_f32_e32 v238, v238, v199
	v_exp_f32_e32 v150, v150
	v_cvt_pk_bf16_f32 v188, v192, v193
	v_cvt_pk_bf16_f32 v189, v194, v195
	v_exp_f32_e32 v151, v151
	v_cvt_pk_bf16_f32 v190, v196, v197
	v_cvt_pk_bf16_f32 v191, v198, v199
	v_exp_f32_e32 v152, v152
	v_exp_f32_e32 v153, v153
	s_nop 0
	s_waitcnt lgkmcnt(6)
	v_mfma_f32_32x32x16_bf16 v[18:33], v[204:207], v[188:191], v[18:33]
	ds_read_b64_tr_b16 v[204:205], v133 offset:55296
	ds_read_b64_tr_b16 v[206:207], v133 offset:56832
	s_waitcnt lgkmcnt(6)
	v_mfma_f32_32x32x16_bf16 v[2:17], v[234:237], v[188:191], v[2:17]
	ds_read_b64_tr_b16 v[234:235], v133 offset:55360
	ds_read_b64_tr_b16 v[236:237], v133 offset:56896
	v_exp_f32_e32 v154, v154
	v_add_f32_e32 v238, v238, v146
	v_add_f32_e32 v238, v238, v147
	v_exp_f32_e32 v155, v155
	v_add_f32_e32 v238, v238, v148
	v_add_f32_e32 v238, v238, v149
	v_exp_f32_e32 v156, v156
	v_add_f32_e32 v238, v238, v150
	v_add_f32_e32 v238, v238, v151
	v_exp_f32_e32 v157, v157
	v_add_f32_e32 v238, v238, v152
	v_add_f32_e32 v238, v238, v153
	v_exp_f32_e32 v158, v158
	v_cvt_pk_bf16_f32 v146, v146, v147
	v_cvt_pk_bf16_f32 v147, v148, v149
	v_exp_f32_e32 v159, v159
	v_cvt_pk_bf16_f32 v148, v150, v151
	v_cvt_pk_bf16_f32 v149, v152, v153
	v_exp_f32_e32 v160, v160
	v_exp_f32_e32 v161, v161
	s_nop 0
	s_waitcnt lgkmcnt(6)
	v_mfma_f32_32x32x16_bf16 v[18:33], v[46:49], v[146:149], v[18:33]
	s_waitcnt lgkmcnt(4)
	v_mfma_f32_32x32x16_bf16 v[2:17], v[200:203], v[146:149], v[2:17]
	v_add_f32_e32 v238, v238, v154
	v_add_f32_e32 v238, v238, v155
	v_add_f32_e32 v238, v238, v156
	v_add_f32_e32 v238, v238, v157
	v_add_f32_e32 v238, v238, v158
	v_add_f32_e32 v238, v238, v159
	v_add_f32_e32 v238, v238, v160
	v_add_f32_e32 v238, v238, v161
	v_cvt_pk_bf16_f32 v150, v154, v155
	v_cvt_pk_bf16_f32 v151, v156, v157
	v_cvt_pk_bf16_f32 v152, v158, v159
	v_cvt_pk_bf16_f32 v153, v160, v161
	s_nop 0
	s_waitcnt lgkmcnt(2)
	v_mfma_f32_32x32x16_bf16 v[18:33], v[204:207], v[150:153], v[18:33]
	s_waitcnt lgkmcnt(0)
	v_mfma_f32_32x32x16_bf16 v[2:17], v[234:237], v[150:153], v[2:17]
	v_fma_f32 v128, v136, v140, v238
	s_cmpk_lt_u32 s27, 0x42
	s_cbranch_scc0 .LBB0_727

; DI void gemm_phase(const Params& p, int layer, int mode, int nrows, char* lds_all) {
;     ...
;   for (int i = jb;; i += nj) {
;     const int srl = i / per, rem = i - srl * per;
;     const int sr = xcd + nx * srl;
;     if (sr >= nsr) break;
;     const int tn = rem >> 1, tm = sr * 2 + (rem & 1);
;     const int m0 = tm * 256, n0 = tn * 256;
.LBB0_833:
	s_lshl_b32 s24, s4, 5
	s_sub_i32 s24, s21, s24
	s_xor_b32 s11, s4, 1
	s_lshl_b32 s11, s11, 3
	s_add_i32 s11, s11, s19
	s_cmp_lt_i32 s11, s36
	s_cbranch_scc0 .Lm2map_old_a
	s_and_b32 s11, s4, 0xfffffffe
	s_bfe_u32 s5, s24, 0x10001
	s_add_i32 s11, s11, s5
	s_lshl_b32 s11, s11, 3
	s_add_i32 s11, s11, s19
	s_lshl_b32 s11, s11, 9
	s_and_b32 s5, s24, 1
	s_lshl_b32 s5, s5, 8
	s_or_b32 s22, s11, s5
	s_lshr_b32 s23, s24, 2
	s_and_b32 s5, s4, 1
	s_lshl_b32 s5, s5, 3
	s_add_i32 s23, s23, s5
	s_lshl_b32 s23, s23, 8
	s_branch .Lm2map_done_a

; #define G5_LOAD(k0)                                                                 \
;   {                                                                                 \
;     _Pragma("unroll") for (int i_ = 0; i_ < 4; ++i_) ra[i_] = ldg16(Ap + (size_t)(i_ * 64) * lda + (k0)); \
;     _Pragma("unroll") for (int i_ = 0; i_ < 4; ++i_) rb[i_] = ldg16(Bp + (size_t)(i_ * 64) * ldb + (k0)); \
;   }
; #define G5_STORE(s)                                                                 \
;   {                                                                                 \
;     _Pragma("unroll") for (int i_ = 0; i_ < 4; ++i_) *(u32x4*)(Sw + (s) * STG + i_ * 64 * GS) = ra[i_]; \
;     _Pragma("unroll") for (int i_ = 0; i_ < 4; ++i_) *(u32x4*)(Sw + (s) * STG + 256 * GS + i_ * 64 * GS) = rb[i_]; \
;   }
; template <typename Epi>
; DI void gemm_tile512(const u16* __restrict__ A, int lda, const u16* __restrict__ Bt, int ldb, int K, char* lds_all, Epi epi) {
;     ...
;   const int nk = K >> 6;
;   __syncthreads();
;   G5_LOAD(0);
;   G5_STORE(0);
;   G5_LOAD(64);
;   __syncthreads();
; DI void gemm_phase(const Params& p, int layer, int mode, int nrows, char* lds_all) {
;     ...
;   for (int i = jb;; i += nj) {
;     const int srl = i / per, rem = i - srl * per;
;     const int sr = xcd + nx * srl;
;     if (sr >= nsr) break;
;     const int tn = rem >> 1, tm = sr * 2 + (rem & 1);
;     const int m0 = tm * 256, n0 = tn * 256;
;     gemm_tile512(A + (size_t)m0 * lda, lda, Bt + (size_t)n0 * ldb, ldb, K, lds_all, [&](int half) {
.Lm2map_done_a:
	s_mul_i32 s4, s22, 0x900
	v_readlane_b32 s8, v250, 46
	s_mul_hi_i32 s5, s22, 0x900
	s_add_u32 s4, s8, s4
	v_readlane_b32 s8, v250, 47
	s_addc_u32 s5, s8, s5
	s_mul_i32 s8, s23, 0x900
	s_mul_hi_i32 s9, s23, 0x900
	s_add_u32 s8, s14, s8
	s_addc_u32 s9, s15, s9
	s_mov_b64 s[26:27], s[4:5]
	s_mov_b64 s[98:99], s[26:27]
	s_mov_b64 s[100:101], s[8:9]
	v_lshrrev_b32_e32 v239, 3, v165
	v_and_b32_e32 v0, 7, v165
	v_mul_u32_u24_e32 v206, 0x900, v239
	v_lshl_add_u32 v206, v0, 4, v206
	v_add_u32_e32 v207, 0x24000, v206
	v_add_u32_e32 v208, 0x48000, v206
	v_add_u32_e32 v238, 0x6c000, v206
	global_load_dwordx4 v[130:133], v206, s[98:99]
	global_load_dwordx4 v[134:137], v207, s[98:99]
	global_load_dwordx4 v[138:141], v208, s[98:99]
	global_load_dwordx4 v[142:145], v238, s[98:99]
	global_load_dwordx4 v[146:149], v206, s[100:101]
	global_load_dwordx4 v[150:153], v207, s[100:101]
	global_load_dwordx4 v[154:157], v208, s[100:101]
	global_load_dwordx4 v[158:161], v238, s[100:101]
	global_load_dwordx4 v[218:221], v206, s[98:99] offset:128
	global_load_dwordx4 v[222:225], v207, s[98:99] offset:128
	global_load_dwordx4 v[226:229], v208, s[98:99] offset:128
	global_load_dwordx4 v[230:233], v238, s[98:99] offset:128
	global_load_dwordx4 v[166:169], v206, s[100:101] offset:128
	global_load_dwordx4 v[170:173], v207, s[100:101] offset:128
	global_load_dwordx4 v[174:177], v208, s[100:101] offset:128
	global_load_dwordx4 v[190:193], v238, s[100:101] offset:128
	s_add_u32 s98, s98, 0x100
	s_addc_u32 s99, s99, 0
	s_add_u32 s100, s100, 0x100
	s_addc_u32 s101, s101, 0
	v_lshrrev_b32_e32 v239, 3, v165
	v_and_b32_e32 v0, 7, v165
	v_mul_u32_u24_e32 v180, 0x90, v239
	v_lshl_add_u32 v180, v0, 4, v180
	v_and_b32_e32 v239, 31, v165
	v_bfe_u32 v0, v165, 5, 1
	v_lshrrev_b32_e32 v179, 8, v165
	v_lshl_or_b32 v178, v179, 7, v239
	v_mul_u32_u24_e32 v178, 0x90, v178
	v_lshl_add_u32 v178, v0, 4, v178
	v_bfe_u32 v179, v165, 6, 2
	v_lshl_or_b32 v179, v179, 6, v239
	v_mul_u32_u24_e32 v179, 0x90, v179
	v_lshl_add_u32 v179, v0, 4, v179
	s_mov_b32 s11, 0x12000
	s_mov_b32 s12, 13
	s_barrier
	s_waitcnt vmcnt(15)
	ds_write_b128 v180, v[130:133]
	s_waitcnt vmcnt(14)
	ds_write_b128 v180, v[134:137] offset:9216
	s_waitcnt vmcnt(13)
	ds_write_b128 v180, v[138:141] offset:18432
	s_waitcnt vmcnt(12)
	ds_write_b128 v180, v[142:145] offset:27648
	s_waitcnt vmcnt(11)
	ds_write_b128 v180, v[146:149] offset:36864
	s_waitcnt vmcnt(10)
	ds_write_b128 v180, v[150:153] offset:46080
	s_waitcnt vmcnt(9)
	ds_write_b128 v180, v[154:157] offset:55296
	s_waitcnt vmcnt(8)
	ds_write_b128 v180, v[158:161] offset:64512
	v_add_u32_e32 v180, 0x12000, v180
	s_waitcnt vmcnt(7)
	ds_write_b128 v180, v[218:221]
	s_waitcnt vmcnt(6)
	ds_write_b128 v180, v[222:225] offset:9216
	s_waitcnt vmcnt(5)
	ds_write_b128 v180, v[226:229] offset:18432
	s_waitcnt vmcnt(4)
	ds_write_b128 v180, v[230:233] offset:27648
	s_waitcnt vmcnt(3)
	ds_write_b128 v180, v[166:169] offset:36864
	s_waitcnt vmcnt(2)
	ds_write_b128 v180, v[170:173] offset:46080
	s_waitcnt vmcnt(1)
	ds_write_b128 v180, v[174:177] offset:55296
	s_waitcnt vmcnt(0)
	ds_write_b128 v180, v[190:193] offset:64512
	s_waitcnt lgkmcnt(0)
	s_branch .Lg3_k_m2

; #define G5_LOAD(k0)                                                                 \
;   {                                                                                 \
;     _Pragma("unroll") for (int i_ = 0; i_ < 4; ++i_) ra[i_] = ldg16(Ap + (size_t)(i_ * 64) * lda + (k0)); \
;     _Pragma("unroll") for (int i_ = 0; i_ < 4; ++i_) rb[i_] = ldg16(Bp + (size_t)(i_ * 64) * ldb + (k0)); \
;   }
; #define G5_STORE(s)                                                                 \
;   {                                                                                 \
;     _Pragma("unroll") for (int i_ = 0; i_ < 4; ++i_) *(u32x4*)(Sw + (s) * STG + i_ * 64 * GS) = ra[i_]; \
;     _Pragma("unroll") for (int i_ = 0; i_ < 4; ++i_) *(u32x4*)(Sw + (s) * STG + 256 * GS + i_ * 64 * GS) = rb[i_]; \
;   }
; template <typename Epi>
; DI void gemm_tile512(const u16* __restrict__ A, int lda, const u16* __restrict__ Bt, int ldb, int K, char* lds_all, Epi epi) {
;     ...
;   const int nk = K >> 6;
;   __syncthreads();
;   G5_LOAD(0);
;   G5_STORE(0);
;   G5_LOAD(64);
;   __syncthreads();
;   for (int kt = 0; kt + 2 < nk; ++kt) {
;     const int cur = kt & 1;
;     G5_COMPUTE(cur);
;     G5_STORE(cur ^ 1);
;     G5_LOAD((kt + 2) << 6);
;     __syncthreads();
;   }
.Lg3_loop_m2:
	s_barrier
	ds_read_b128 v[194:197], v179 offset:36864
	ds_read_b128 v[166:169], v178
	v_mfma_f32_32x32x16_bf16 v[114:129], v[234:237], v[218:221], v[114:129]
	ds_read_b128 v[198:201], v179 offset:41472
	v_mfma_f32_32x32x16_bf16 v[98:113], v[202:205], v[218:221], v[98:113]
	ds_read_b128 v[170:173], v178 offset:4608
	v_mfma_f32_32x32x16_bf16 v[82:97], v[234:237], v[222:225], v[82:97]
	ds_read_b128 v[174:177], v178 offset:9216
	v_mfma_f32_32x32x16_bf16 v[66:81], v[202:205], v[222:225], v[66:81]
	ds_read_b128 v[190:193], v178 offset:13824
	v_mfma_f32_32x32x16_bf16 v[50:65], v[234:237], v[226:229], v[50:65]
	v_mfma_f32_32x32x16_bf16 v[34:49], v[202:205], v[226:229], v[34:49]
	v_mfma_f32_32x32x16_bf16 v[18:33], v[234:237], v[230:233], v[18:33]
	v_mfma_f32_32x32x16_bf16 v[2:17], v[202:205], v[230:233], v[2:17]
	s_waitcnt lgkmcnt(4)
	v_mfma_f32_32x32x16_bf16 v[114:129], v[194:197], v[166:169], v[114:129]
	ds_read_b128 v[234:237], v179 offset:36896
	s_waitcnt lgkmcnt(4)
	v_mfma_f32_32x32x16_bf16 v[98:113], v[198:201], v[166:169], v[98:113]
	ds_read_b128 v[218:221], v178 offset:32
	s_waitcnt vmcnt(7)
	ds_write_b128 v180, v[130:133]
	global_load_dwordx4 v[130:133], v206, s[98:99]
	s_waitcnt lgkmcnt(5)
	v_mfma_f32_32x32x16_bf16 v[82:97], v[194:197], v[170:173], v[82:97]
	ds_read_b128 v[202:205], v179 offset:41504
	v_mfma_f32_32x32x16_bf16 v[66:81], v[198:201], v[170:173], v[66:81]
	ds_read_b128 v[222:225], v178 offset:4640
	s_waitcnt vmcnt(7)
	ds_write_b128 v180, v[134:137] offset:9216
	global_load_dwordx4 v[134:137], v207, s[98:99]
	s_waitcnt lgkmcnt(7)
	v_mfma_f32_32x32x16_bf16 v[50:65], v[194:197], v[174:177], v[50:65]
	ds_read_b128 v[226:229], v178 offset:9248
	v_mfma_f32_32x32x16_bf16 v[34:49], v[198:201], v[174:177], v[34:49]
	ds_read_b128 v[230:233], v178 offset:13856
	s_waitcnt vmcnt(7)
	ds_write_b128 v180, v[138:141] offset:18432
	global_load_dwordx4 v[138:141], v208, s[98:99]
	s_waitcnt lgkmcnt(9)
	v_mfma_f32_32x32x16_bf16 v[18:33], v[194:197], v[190:193], v[18:33]
	v_mfma_f32_32x32x16_bf16 v[2:17], v[198:201], v[190:193], v[2:17]
	s_waitcnt vmcnt(7)
	ds_write_b128 v180, v[142:145] offset:27648
	global_load_dwordx4 v[142:145], v238, s[98:99]
	s_waitcnt lgkmcnt(8)
	v_mfma_f32_32x32x16_bf16 v[114:129], v[234:237], v[218:221], v[114:129]
	ds_read_b128 v[194:197], v179 offset:36928
	s_waitcnt lgkmcnt(7)
	v_mfma_f32_32x32x16_bf16 v[98:113], v[202:205], v[218:221], v[98:113]
	ds_read_b128 v[166:169], v178 offset:64
	s_waitcnt vmcnt(7)
	ds_write_b128 v180, v[146:149] offset:36864
	global_load_dwordx4 v[146:149], v206, s[100:101]
	s_waitcnt lgkmcnt(8)
	v_mfma_f32_32x32x16_bf16 v[82:97], v[234:237], v[222:225], v[82:97]
	ds_read_b128 v[198:201], v179 offset:41536
	v_mfma_f32_32x32x16_bf16 v[66:81], v[202:205], v[222:225], v[66:81]
	ds_read_b128 v[170:173], v178 offset:4672
	s_waitcnt vmcnt(7)
	ds_write_b128 v180, v[150:153] offset:46080
	global_load_dwordx4 v[150:153], v207, s[100:101]
	s_waitcnt lgkmcnt(9)
	v_mfma_f32_32x32x16_bf16 v[50:65], v[234:237], v[226:229], v[50:65]
	ds_read_b128 v[174:177], v178 offset:9280
	v_mfma_f32_32x32x16_bf16 v[34:49], v[202:205], v[226:229], v[34:49]
	ds_read_b128 v[190:193], v178 offset:13888
	s_waitcnt vmcnt(7)
	ds_write_b128 v180, v[154:157] offset:55296
	global_load_dwordx4 v[154:157], v208, s[100:101]
	s_waitcnt lgkmcnt(11)
	v_mfma_f32_32x32x16_bf16 v[18:33], v[234:237], v[230:233], v[18:33]
	v_mfma_f32_32x32x16_bf16 v[2:17], v[202:205], v[230:233], v[2:17]
	s_waitcnt vmcnt(7)
	ds_write_b128 v180, v[158:161] offset:64512
	global_load_dwordx4 v[158:161], v238, s[100:101]
	v_subrev_u32_e32 v180, s11, v180
	s_waitcnt lgkmcnt(8)
	v_mfma_f32_32x32x16_bf16 v[114:129], v[194:197], v[166:169], v[114:129]
	ds_read_b128 v[234:237], v179 offset:36960
	s_waitcnt lgkmcnt(7)
	v_mfma_f32_32x32x16_bf16 v[98:113], v[198:201], v[166:169], v[98:113]
	ds_read_b128 v[218:221], v178 offset:96
	s_waitcnt lgkmcnt(7)
	v_mfma_f32_32x32x16_bf16 v[82:97], v[194:197], v[170:173], v[82:97]
	ds_read_b128 v[202:205], v179 offset:41568
	v_mfma_f32_32x32x16_bf16 v[66:81], v[198:201], v[170:173], v[66:81]
	ds_read_b128 v[222:225], v178 offset:4704
	s_waitcnt lgkmcnt(7)
	v_mfma_f32_32x32x16_bf16 v[50:65], v[194:197], v[174:177], v[50:65]
	ds_read_b128 v[226:229], v178 offset:9312
	v_mfma_f32_32x32x16_bf16 v[34:49], v[198:201], v[174:177], v[34:49]
	ds_read_b128 v[230:233], v178 offset:13920
	v_add_u32_e32 v178, s11, v178
	v_add_u32_e32 v179, s11, v179
	s_waitcnt lgkmcnt(8)
	v_mfma_f32_32x32x16_bf16 v[18:33], v[194:197], v[190:193], v[18:33]
	v_mfma_f32_32x32x16_bf16 v[2:17], v[198:201], v[190:193], v[2:17]
	s_sub_u32 s11, 0, s11
	s_add_u32 s98, s98, 0x80
	s_addc_u32 s99, s99, 0
	s_add_u32 s100, s100, 0x80
	s_addc_u32 s101, s101, 0
	s_waitcnt lgkmcnt(0)
	s_sub_u32 s12, s12, 1
	s_cmp_lg_u32 s12, 0
	s_cbranch_scc1 .Lg3_loop_m2
	s_barrier
; #define G5_LOAD(k0)                                                                 \
;   {                                                                                 \
;     _Pragma("unroll") for (int i_ = 0; i_ < 4; ++i_) ra[i_] = ldg16(Ap + (size_t)(i_ * 64) * lda + (k0)); \
;     _Pragma("unroll") for (int i_ = 0; i_ < 4; ++i_) rb[i_] = ldg16(Bp + (size_t)(i_ * 64) * ldb + (k0)); \
;   }
; #define G5_STORE(s)                                                                 \
;   {                                                                                 \
;     _Pragma("unroll") for (int i_ = 0; i_ < 4; ++i_) *(u32x4*)(Sw + (s) * STG + i_ * 64 * GS) = ra[i_]; \
;     _Pragma("unroll") for (int i_ = 0; i_ < 4; ++i_) *(u32x4*)(Sw + (s) * STG + 256 * GS + i_ * 64 * GS) = rb[i_]; \
;   }
; template <typename Epi>
; DI void gemm_tile512(const u16* __restrict__ A, int lda, const u16* __restrict__ Bt, int ldb, int K, char* lds_all, Epi epi) {
;     ...
;   for (int kt = 0; kt + 2 < nk; ++kt) {
;     const int cur = kt & 1;
;     G5_COMPUTE(cur);
;     G5_STORE(cur ^ 1);
;     G5_LOAD((kt + 2) << 6);
;     __syncthreads();
;   }
;   {
;     const int cur = (nk - 2) & 1;
;     G5_COMPUTE(cur);
;     G5_STORE(cur ^ 1);
;     __syncthreads();
	ds_read_b128 v[194:197], v179 offset:36864
	ds_read_b128 v[166:169], v178
	v_mfma_f32_32x32x16_bf16 v[114:129], v[234:237], v[218:221], v[114:129]
	ds_read_b128 v[198:201], v179 offset:41472
	v_mfma_f32_32x32x16_bf16 v[98:113], v[202:205], v[218:221], v[98:113]
	ds_read_b128 v[170:173], v178 offset:4608
	v_mfma_f32_32x32x16_bf16 v[82:97], v[234:237], v[222:225], v[82:97]
	ds_read_b128 v[174:177], v178 offset:9216
	v_mfma_f32_32x32x16_bf16 v[66:81], v[202:205], v[222:225], v[66:81]
	ds_read_b128 v[190:193], v178 offset:13824
	v_mfma_f32_32x32x16_bf16 v[50:65], v[234:237], v[226:229], v[50:65]
	v_mfma_f32_32x32x16_bf16 v[34:49], v[202:205], v[226:229], v[34:49]
	v_mfma_f32_32x32x16_bf16 v[18:33], v[234:237], v[230:233], v[18:33]
	v_mfma_f32_32x32x16_bf16 v[2:17], v[202:205], v[230:233], v[2:17]
	s_waitcnt lgkmcnt(4)
	v_mfma_f32_32x32x16_bf16 v[114:129], v[194:197], v[166:169], v[114:129]
	ds_read_b128 v[234:237], v179 offset:36896
	s_waitcnt lgkmcnt(4)
	v_mfma_f32_32x32x16_bf16 v[98:113], v[198:201], v[166:169], v[98:113]
	ds_read_b128 v[218:221], v178 offset:32
	s_waitcnt vmcnt(7)
	ds_write_b128 v180, v[130:133]
	s_waitcnt lgkmcnt(5)
	v_mfma_f32_32x32x16_bf16 v[82:97], v[194:197], v[170:173], v[82:97]
	ds_read_b128 v[202:205], v179 offset:41504
	v_mfma_f32_32x32x16_bf16 v[66:81], v[198:201], v[170:173], v[66:81]
	ds_read_b128 v[222:225], v178 offset:4640
	s_waitcnt vmcnt(6)
	ds_write_b128 v180, v[134:137] offset:9216
	s_waitcnt lgkmcnt(7)
	v_mfma_f32_32x32x16_bf16 v[50:65], v[194:197], v[174:177], v[50:65]
	ds_read_b128 v[226:229], v178 offset:9248
	v_mfma_f32_32x32x16_bf16 v[34:49], v[198:201], v[174:177], v[34:49]
	ds_read_b128 v[230:233], v178 offset:13856
	s_waitcnt vmcnt(5)
	ds_write_b128 v180, v[138:141] offset:18432
	s_waitcnt lgkmcnt(9)
	v_mfma_f32_32x32x16_bf16 v[18:33], v[194:197], v[190:193], v[18:33]
	v_mfma_f32_32x32x16_bf16 v[2:17], v[198:201], v[190:193], v[2:17]
	s_waitcnt vmcnt(4)
	ds_write_b128 v180, v[142:145] offset:27648
	s_waitcnt lgkmcnt(8)
	v_mfma_f32_32x32x16_bf16 v[114:129], v[234:237], v[218:221], v[114:129]
	ds_read_b128 v[194:197], v179 offset:36928
	s_waitcnt lgkmcnt(7)
	v_mfma_f32_32x32x16_bf16 v[98:113], v[202:205], v[218:221], v[98:113]
	ds_read_b128 v[166:169], v178 offset:64
	s_waitcnt vmcnt(3)
	ds_write_b128 v180, v[146:149] offset:36864
	s_waitcnt lgkmcnt(8)
	v_mfma_f32_32x32x16_bf16 v[82:97], v[234:237], v[222:225], v[82:97]
	ds_read_b128 v[198:201], v179 offset:41536
	v_mfma_f32_32x32x16_bf16 v[66:81], v[202:205], v[222:225], v[66:81]
	ds_read_b128 v[170:173], v178 offset:4672
	s_waitcnt vmcnt(2)
	ds_write_b128 v180, v[150:153] offset:46080
	s_waitcnt lgkmcnt(9)
	v_mfma_f32_32x32x16_bf16 v[50:65], v[234:237], v[226:229], v[50:65]
	ds_read_b128 v[174:177], v178 offset:9280
	v_mfma_f32_32x32x16_bf16 v[34:49], v[202:205], v[226:229], v[34:49]
	ds_read_b128 v[190:193], v178 offset:13888
	s_waitcnt vmcnt(1)
	ds_write_b128 v180, v[154:157] offset:55296
	s_waitcnt lgkmcnt(11)
	v_mfma_f32_32x32x16_bf16 v[18:33], v[234:237], v[230:233], v[18:33]
	v_mfma_f32_32x32x16_bf16 v[2:17], v[202:205], v[230:233], v[2:17]
	s_waitcnt vmcnt(0)
	ds_write_b128 v180, v[158:161] offset:64512
	v_subrev_u32_e32 v180, s11, v180
	s_waitcnt lgkmcnt(8)
	v_mfma_f32_32x32x16_bf16 v[114:129], v[194:197], v[166:169], v[114:129]
	ds_read_b128 v[234:237], v179 offset:36960
	s_waitcnt lgkmcnt(7)
	v_mfma_f32_32x32x16_bf16 v[98:113], v[198:201], v[166:169], v[98:113]
	ds_read_b128 v[218:221], v178 offset:96
	s_waitcnt lgkmcnt(7)
	v_mfma_f32_32x32x16_bf16 v[82:97], v[194:197], v[170:173], v[82:97]
	ds_read_b128 v[202:205], v179 offset:41568
	v_mfma_f32_32x32x16_bf16 v[66:81], v[198:201], v[170:173], v[66:81]
	ds_read_b128 v[222:225], v178 offset:4704
	s_waitcnt lgkmcnt(7)
	v_mfma_f32_32x32x16_bf16 v[50:65], v[194:197], v[174:177], v[50:65]
	ds_read_b128 v[226:229], v178 offset:9312
	v_mfma_f32_32x32x16_bf16 v[34:49], v[198:201], v[174:177], v[34:49]
	ds_read_b128 v[230:233], v178 offset:13920
	v_add_u32_e32 v178, s11, v178
	v_add_u32_e32 v179, s11, v179
	s_waitcnt lgkmcnt(8)
	v_mfma_f32_32x32x16_bf16 v[18:33], v[194:197], v[190:193], v[18:33]
	v_mfma_f32_32x32x16_bf16 v[2:17], v[198:201], v[190:193], v[2:17]
	s_sub_u32 s11, 0, s11
	s_add_u32 s98, s98, 0x80
	s_addc_u32 s99, s99, 0
	s_add_u32 s100, s100, 0x80
	s_addc_u32 s101, s101, 0
	s_waitcnt lgkmcnt(0)
	s_barrier
; #define G5_STORE(s)                                                                 \
;   {                                                                                 \
;     _Pragma("unroll") for (int i_ = 0; i_ < 4; ++i_) *(u32x4*)(Sw + (s) * STG + i_ * 64 * GS) = ra[i_]; \
;     _Pragma("unroll") for (int i_ = 0; i_ < 4; ++i_) *(u32x4*)(Sw + (s) * STG + 256 * GS + i_ * 64 * GS) = rb[i_]; \
;   }
; template <typename Epi>
; DI void gemm_tile512(const u16* __restrict__ A, int lda, const u16* __restrict__ Bt, int ldb, int K, char* lds_all, Epi epi) {
;     ...
;   {
;     const int cur = (nk - 2) & 1;
;     G5_COMPUTE(cur);
;     G5_STORE(cur ^ 1);
;     __syncthreads();
;     G5_COMPUTE(cur ^ 1);
;   }
; DI void gemm_phase(const Params& p, int layer, int mode, int nrows, char* lds_all) {
;     ...
;   for (int i = jb;; i += nj) {
;     const int srl = i / per, rem = i - srl * per;
;     const int sr = xcd + nx * srl;
;     if (sr >= nsr) break;
;     const int tn = rem >> 1, tm = sr * 2 + (rem & 1);
;     const int m0 = tm * 256, n0 = tn * 256;
	ds_read_b128 v[194:197], v179 offset:36864
	ds_read_b128 v[166:169], v178
	v_mfma_f32_32x32x16_bf16 v[114:129], v[234:237], v[218:221], v[114:129]
	ds_read_b128 v[198:201], v179 offset:41472
	v_mfma_f32_32x32x16_bf16 v[98:113], v[202:205], v[218:221], v[98:113]
	ds_read_b128 v[170:173], v178 offset:4608
	v_mfma_f32_32x32x16_bf16 v[82:97], v[234:237], v[222:225], v[82:97]
	ds_read_b128 v[174:177], v178 offset:9216
	v_mfma_f32_32x32x16_bf16 v[66:81], v[202:205], v[222:225], v[66:81]
	ds_read_b128 v[190:193], v178 offset:13824
	v_mfma_f32_32x32x16_bf16 v[50:65], v[234:237], v[226:229], v[50:65]
	v_mfma_f32_32x32x16_bf16 v[34:49], v[202:205], v[226:229], v[34:49]
	v_mfma_f32_32x32x16_bf16 v[18:33], v[234:237], v[230:233], v[18:33]
	v_mfma_f32_32x32x16_bf16 v[2:17], v[202:205], v[230:233], v[2:17]
	s_waitcnt lgkmcnt(4)
	v_mfma_f32_32x32x16_bf16 v[114:129], v[194:197], v[166:169], v[114:129]
	ds_read_b128 v[234:237], v179 offset:36896
	s_waitcnt lgkmcnt(4)
	v_mfma_f32_32x32x16_bf16 v[98:113], v[198:201], v[166:169], v[98:113]
	ds_read_b128 v[218:221], v178 offset:32
	s_waitcnt lgkmcnt(4)
	v_mfma_f32_32x32x16_bf16 v[82:97], v[194:197], v[170:173], v[82:97]
	ds_read_b128 v[202:205], v179 offset:41504
	v_mfma_f32_32x32x16_bf16 v[66:81], v[198:201], v[170:173], v[66:81]
	ds_read_b128 v[222:225], v178 offset:4640
	s_waitcnt lgkmcnt(5)
	v_mfma_f32_32x32x16_bf16 v[50:65], v[194:197], v[174:177], v[50:65]
	ds_read_b128 v[226:229], v178 offset:9248
	v_mfma_f32_32x32x16_bf16 v[34:49], v[198:201], v[174:177], v[34:49]
	ds_read_b128 v[230:233], v178 offset:13856
	s_waitcnt lgkmcnt(6)
	v_mfma_f32_32x32x16_bf16 v[18:33], v[194:197], v[190:193], v[18:33]
	v_mfma_f32_32x32x16_bf16 v[2:17], v[198:201], v[190:193], v[2:17]
	s_waitcnt lgkmcnt(4)
	v_mfma_f32_32x32x16_bf16 v[114:129], v[234:237], v[218:221], v[114:129]
	ds_read_b128 v[194:197], v179 offset:36928
	s_waitcnt lgkmcnt(4)
	v_mfma_f32_32x32x16_bf16 v[98:113], v[202:205], v[218:221], v[98:113]
	ds_read_b128 v[166:169], v178 offset:64
	s_waitcnt lgkmcnt(4)
	v_mfma_f32_32x32x16_bf16 v[82:97], v[234:237], v[222:225], v[82:97]
	ds_read_b128 v[198:201], v179 offset:41536
	v_mfma_f32_32x32x16_bf16 v[66:81], v[202:205], v[222:225], v[66:81]
	ds_read_b128 v[170:173], v178 offset:4672
	s_waitcnt lgkmcnt(5)
	v_mfma_f32_32x32x16_bf16 v[50:65], v[234:237], v[226:229], v[50:65]
	ds_read_b128 v[174:177], v178 offset:9280
	v_mfma_f32_32x32x16_bf16 v[34:49], v[202:205], v[226:229], v[34:49]
	ds_read_b128 v[190:193], v178 offset:13888
	s_waitcnt lgkmcnt(6)
	v_mfma_f32_32x32x16_bf16 v[18:33], v[234:237], v[230:233], v[18:33]
	v_mfma_f32_32x32x16_bf16 v[2:17], v[202:205], v[230:233], v[2:17]
	s_waitcnt lgkmcnt(4)
	v_mfma_f32_32x32x16_bf16 v[114:129], v[194:197], v[166:169], v[114:129]
	ds_read_b128 v[234:237], v179 offset:36960
	s_waitcnt lgkmcnt(4)
	v_mfma_f32_32x32x16_bf16 v[98:113], v[198:201], v[166:169], v[98:113]
	ds_read_b128 v[218:221], v178 offset:96
	s_waitcnt lgkmcnt(4)
	v_mfma_f32_32x32x16_bf16 v[82:97], v[194:197], v[170:173], v[82:97]
	ds_read_b128 v[202:205], v179 offset:41568
	v_mfma_f32_32x32x16_bf16 v[66:81], v[198:201], v[170:173], v[66:81]
	ds_read_b128 v[222:225], v178 offset:4704
	s_waitcnt lgkmcnt(5)
	v_mfma_f32_32x32x16_bf16 v[50:65], v[194:197], v[174:177], v[50:65]
	ds_read_b128 v[226:229], v178 offset:9312
	v_mfma_f32_32x32x16_bf16 v[34:49], v[198:201], v[174:177], v[34:49]
	ds_read_b128 v[230:233], v178 offset:13920
	s_waitcnt lgkmcnt(6)
	v_mfma_f32_32x32x16_bf16 v[18:33], v[194:197], v[190:193], v[18:33]
	v_mfma_f32_32x32x16_bf16 v[2:17], v[198:201], v[190:193], v[2:17]
	s_waitcnt lgkmcnt(0)
	v_mfma_f32_32x32x16_bf16 v[114:129], v[234:237], v[218:221], v[114:129]
	v_mfma_f32_32x32x16_bf16 v[98:113], v[202:205], v[218:221], v[98:113]
	v_mfma_f32_32x32x16_bf16 v[82:97], v[234:237], v[222:225], v[82:97]
	v_mfma_f32_32x32x16_bf16 v[66:81], v[202:205], v[222:225], v[66:81]
	v_mfma_f32_32x32x16_bf16 v[50:65], v[234:237], v[226:229], v[50:65]
	v_mfma_f32_32x32x16_bf16 v[34:49], v[202:205], v[226:229], v[34:49]
	v_mfma_f32_32x32x16_bf16 v[18:33], v[234:237], v[230:233], v[18:33]
	v_mfma_f32_32x32x16_bf16 v[2:17], v[202:205], v[230:233], v[2:17]
	s_mul_i32 s10, s22, 0x2100
	s_lshl_b32 s20, s23, 1
	s_add_u32 s10, s10, s20
	v_lshrrev_b32_e32 v237, 5, v165
	v_and_b32_e32 v194, 31, v165
	v_mul_u32_u24_e32 v234, 0x2100, v237
	v_lshl_add_u32 v234, v194, 4, v234
	v_add_u32_e32 v234, s10, v234
	s_add_i32 s21, s21, s18
	s_ashr_i32 s4, s21, 31
	s_lshr_b32 s4, s4, 27
	s_add_i32 s4, s21, s4
	s_ashr_i32 s4, s4, 5
	v_readlane_b32 s5, v252, 2
	v_readlane_b32 s8, v252, 6
	s_lshl_b32 s5, s4, s5
	s_add_i32 s17, s17, s8
	v_readlane_b32 s8, v252, 9
	s_add_i32 s5, s5, s19
	s_add_i32 s16, s16, s8
	s_cmp_lt_i32 s5, s36
	s_cselect_b32 s10, 1, 0
	s_cmp_eq_u32 s10, 0
	s_cbranch_scc1 .Lg3_nonext_m2
	s_lshl_b32 s24, s4, 5
	s_sub_i32 s24, s21, s24
	s_xor_b32 s11, s4, 1
	s_lshl_b32 s11, s11, 3
	s_add_i32 s11, s11, s19
	s_cmp_lt_i32 s11, s36
	s_cbranch_scc0 .Lm2map_old_b
	s_and_b32 s11, s4, 0xfffffffe
	s_bfe_u32 s5, s24, 0x10001
	s_add_i32 s11, s11, s5
	s_lshl_b32 s11, s11, 3
	s_add_i32 s11, s11, s19
	s_lshl_b32 s11, s11, 9
	s_and_b32 s5, s24, 1
	s_lshl_b32 s5, s5, 8
	s_or_b32 s22, s11, s5
	s_lshr_b32 s23, s24, 2
	s_and_b32 s5, s4, 1
	s_lshl_b32 s5, s5, 3
	s_add_i32 s23, s23, s5
	s_lshl_b32 s23, s23, 8
	s_branch .Lm2map_done_b

; #define G5_LOAD(k0)                                                                 \
;   {                                                                                 \
;     _Pragma("unroll") for (int i_ = 0; i_ < 4; ++i_) ra[i_] = ldg16(Ap + (size_t)(i_ * 64) * lda + (k0)); \
;     _Pragma("unroll") for (int i_ = 0; i_ < 4; ++i_) rb[i_] = ldg16(Bp + (size_t)(i_ * 64) * ldb + (k0)); \
;   }
; #define G5_STORE(s)                                                                 \
;   {                                                                                 \
;     _Pragma("unroll") for (int i_ = 0; i_ < 4; ++i_) *(u32x4*)(Sw + (s) * STG + i_ * 64 * GS) = ra[i_]; \
;     _Pragma("unroll") for (int i_ = 0; i_ < 4; ++i_) *(u32x4*)(Sw + (s) * STG + 256 * GS + i_ * 64 * GS) = rb[i_]; \
;   }
; template <typename Epi>
; DI void gemm_tile512(const u16* __restrict__ A, int lda, const u16* __restrict__ Bt, int ldb, int K, char* lds_all, Epi epi) {
;     ...
;   const int nk = K >> 6;
;   __syncthreads();
;   G5_LOAD(0);
;   G5_STORE(0);
;   G5_LOAD(64);
; DI void gemm_phase(const Params& p, int layer, int mode, int nrows, char* lds_all) {
;     ...
;   for (int i = jb;; i += nj) {
;     const int srl = i / per, rem = i - srl * per;
;     const int sr = xcd + nx * srl;
;     if (sr >= nsr) break;
;     const int tn = rem >> 1, tm = sr * 2 + (rem & 1);
;     const int m0 = tm * 256, n0 = tn * 256;
;     gemm_tile512(A + (size_t)m0 * lda, lda, Bt + (size_t)n0 * ldb, ldb, K, lds_all, [&](int half) {
.Lm2map_done_b:
	s_mul_i32 s4, s22, 0x900
	v_readlane_b32 s8, v250, 46
	s_mul_hi_i32 s5, s22, 0x900
	s_add_u32 s4, s8, s4
	v_readlane_b32 s8, v250, 47
	s_addc_u32 s5, s8, s5
	s_mul_i32 s8, s23, 0x900
	s_mul_hi_i32 s9, s23, 0x900
	s_add_u32 s8, s14, s8
	s_addc_u32 s9, s15, s9
	s_mov_b64 s[26:27], s[4:5]
	s_mov_b64 s[98:99], s[26:27]
	s_mov_b64 s[100:101], s[8:9]
	v_lshrrev_b32_e32 v239, 3, v165
	v_and_b32_e32 v0, 7, v165
	v_mul_u32_u24_e32 v206, 0x900, v239
	v_lshl_add_u32 v206, v0, 4, v206
	v_add_u32_e32 v207, 0x24000, v206
	v_add_u32_e32 v208, 0x48000, v206
	v_add_u32_e32 v238, 0x6c000, v206
	global_load_dwordx4 v[130:133], v206, s[98:99]
	global_load_dwordx4 v[134:137], v207, s[98:99]
	global_load_dwordx4 v[138:141], v208, s[98:99]
	global_load_dwordx4 v[142:145], v238, s[98:99]
	global_load_dwordx4 v[146:149], v206, s[100:101]
	global_load_dwordx4 v[150:153], v207, s[100:101]
	global_load_dwordx4 v[154:157], v208, s[100:101]
	global_load_dwordx4 v[158:161], v238, s[100:101]
	global_load_dwordx4 v[218:221], v206, s[98:99] offset:128
	global_load_dwordx4 v[222:225], v207, s[98:99] offset:128
	global_load_dwordx4 v[226:229], v208, s[98:99] offset:128
	global_load_dwordx4 v[230:233], v238, s[98:99] offset:128
	global_load_dwordx4 v[166:169], v206, s[100:101] offset:128
	global_load_dwordx4 v[170:173], v207, s[100:101] offset:128
	global_load_dwordx4 v[174:177], v208, s[100:101] offset:128
	global_load_dwordx4 v[190:193], v238, s[100:101] offset:128
	s_add_u32 s98, s98, 0x100
	s_addc_u32 s99, s99, 0
	s_add_u32 s100, s100, 0x100
	s_addc_u32 s101, s101, 0
